# grid barrier: non-last workgroups spin on the top-level generation word instead of the per-XCD relay word
# baseline (speedup 1.0000x reference)
.LBB0_178:
	s_or_b64 exec, exec, s[6:7]
	v_cvt_f32_u32_e32 v4, v2
	s_waitcnt vmcnt(0)
	v_readfirstlane_b32 s2, v3
	v_sub_u32_e32 v3, 0, v2
	v_rcp_iflag_f32_e32 v4, v4
	v_add_u32_e32 v5, s2, v1
	v_mul_f32_e32 v4, 0x4f7ffffe, v4
	v_cvt_u32_f32_e32 v4, v4
	v_mul_lo_u32 v1, v3, v4
	v_mul_hi_u32 v1, v4, v1
	v_add_u32_e32 v1, v4, v1
	v_mul_hi_u32 v1, v5, v1
	v_mul_lo_u32 v3, v1, v2
	v_sub_u32_e32 v3, v5, v3
	v_add_u32_e32 v4, 1, v1
	v_cmp_ge_u32_e32 vcc, v3, v2
	s_nop 1
	v_cndmask_b32_e32 v1, v1, v4, vcc
	v_sub_u32_e32 v4, v3, v2
	v_cndmask_b32_e32 v3, v3, v4, vcc
	v_add_u32_e32 v4, 1, v1
	v_cmp_ge_u32_e32 vcc, v3, v2
	v_add_u32_e32 v3, 1, v5
	s_nop 0
	v_cndmask_b32_e32 v1, v1, v4, vcc
	v_mul_lo_u32 v4, v2, v1
	v_add_u32_e32 v2, v4, v2
	v_cmp_ne_u32_e32 vcc, v3, v2
	s_and_saveexec_b64 s[2:3], vcc
	s_xor_b64 s[2:3], exec, s[2:3]
	s_cbranch_execz .LBB0_192
	s_waitcnt lgkmcnt(0)
	v_mov_b32_e32 v0, 0x2000
	global_load_dword v0, v0, s[4:5] offset:1024 sc1
	s_add_u32 s12, s4, 0x2400
	s_addc_u32 s13, s5, 0
	s_waitcnt vmcnt(0)
	v_cmp_eq_u32_e32 vcc, v0, v1
	s_and_saveexec_b64 s[6:7], vcc
	s_cbranch_execz .LBB0_191
	s_add_u32 s10, s8, 0x8200
	s_addc_u32 s11, s9, 0
	s_add_u32 s12, s8, 0xb500
	s_addc_u32 s13, s9, 0
	s_mov_b32 s21, 1
	s_mov_b64 s[14:15], 0
	v_mov_b32_e32 v0, 0
	s_branch .LBB0_182

.LBB0_335:
	s_or_b64 exec, exec, s[8:9]
	v_cvt_f32_u32_e32 v4, v2
	s_waitcnt vmcnt(0)
	v_readfirstlane_b32 s2, v3
	v_sub_u32_e32 v3, 0, v2
	v_rcp_iflag_f32_e32 v4, v4
	v_add_u32_e32 v5, s2, v1
	v_mul_f32_e32 v4, 0x4f7ffffe, v4
	v_cvt_u32_f32_e32 v4, v4
	v_mul_lo_u32 v1, v3, v4
	v_mul_hi_u32 v1, v4, v1
	v_add_u32_e32 v1, v4, v1
	v_mul_hi_u32 v1, v5, v1
	v_mul_lo_u32 v3, v1, v2
	v_sub_u32_e32 v3, v5, v3
	v_add_u32_e32 v4, 1, v1
	v_cmp_ge_u32_e32 vcc, v3, v2
	s_nop 1
	v_cndmask_b32_e32 v1, v1, v4, vcc
	v_sub_u32_e32 v4, v3, v2
	v_cndmask_b32_e32 v3, v3, v4, vcc
	v_add_u32_e32 v4, 1, v1
	v_cmp_ge_u32_e32 vcc, v3, v2
	v_add_u32_e32 v3, 1, v5
	s_nop 0
	v_cndmask_b32_e32 v1, v1, v4, vcc
	v_mul_lo_u32 v4, v2, v1
	v_add_u32_e32 v2, v4, v2
	v_cmp_ne_u32_e32 vcc, v3, v2
	s_and_saveexec_b64 s[2:3], vcc
	s_xor_b64 s[2:3], exec, s[2:3]
	s_cbranch_execz .LBB0_349
	s_waitcnt lgkmcnt(0)
	v_mov_b32_e32 v0, 0x2000
	global_load_dword v0, v0, s[6:7] offset:1024 sc1
	s_add_u32 s14, s6, 0x2400
	s_addc_u32 s15, s7, 0
	s_waitcnt vmcnt(0)
	v_cmp_eq_u32_e32 vcc, v0, v1
	s_and_saveexec_b64 s[8:9], vcc
	s_cbranch_execz .LBB0_348
	s_add_u32 s12, s0, 0x8200
	s_addc_u32 s13, s1, 0
	s_add_u32 s14, s0, 0xb500
	s_addc_u32 s15, s1, 0
	s_mov_b32 s28, 1
	s_mov_b64 s[16:17], 0
	v_mov_b32_e32 v0, 0
	s_branch .LBB0_339

.LBB0_657:
	s_or_b64 exec, exec, s[6:7]
	v_cvt_f32_u32_e32 v4, v2
	s_waitcnt vmcnt(0)
	v_readfirstlane_b32 s2, v3
	v_sub_u32_e32 v3, 0, v2
	v_rcp_iflag_f32_e32 v4, v4
	v_add_u32_e32 v5, s2, v1
	v_mul_f32_e32 v4, 0x4f7ffffe, v4
	v_cvt_u32_f32_e32 v4, v4
	v_mul_lo_u32 v1, v3, v4
	v_mul_hi_u32 v1, v4, v1
	v_add_u32_e32 v1, v4, v1
	v_mul_hi_u32 v1, v5, v1
	v_mul_lo_u32 v3, v1, v2
	v_sub_u32_e32 v3, v5, v3
	v_add_u32_e32 v4, 1, v1
	v_cmp_ge_u32_e32 vcc, v3, v2
	s_nop 1
	v_cndmask_b32_e32 v1, v1, v4, vcc
	v_sub_u32_e32 v4, v3, v2
	v_cndmask_b32_e32 v3, v3, v4, vcc
	v_add_u32_e32 v4, 1, v1
	v_cmp_ge_u32_e32 vcc, v3, v2
	v_add_u32_e32 v3, 1, v5
	s_nop 0
	v_cndmask_b32_e32 v1, v1, v4, vcc
	v_mul_lo_u32 v4, v2, v1
	v_add_u32_e32 v2, v4, v2
	v_cmp_ne_u32_e32 vcc, v3, v2
	s_and_saveexec_b64 s[2:3], vcc
	s_xor_b64 s[2:3], exec, s[2:3]
	s_cbranch_execz .LBB0_671
	s_waitcnt lgkmcnt(0)
	v_mov_b32_e32 v0, 0x2000
	global_load_dword v0, v0, s[4:5] offset:1024 sc1
	s_add_u32 s14, s4, 0x2400
	s_addc_u32 s15, s5, 0
	s_waitcnt vmcnt(0)
	v_cmp_eq_u32_e32 vcc, v0, v1
	s_and_saveexec_b64 s[6:7], vcc
	s_cbranch_execz .LBB0_670
	s_add_u32 s12, s8, 0x8200
	s_addc_u32 s13, s9, 0
	s_add_u32 s14, s8, 0xb500
	s_addc_u32 s15, s9, 0
	s_mov_b32 s28, 1
	s_mov_b64 s[16:17], 0
	v_mov_b32_e32 v0, 0
	s_branch .LBB0_661

.LBB0_873:
	s_or_b64 exec, exec, s[6:7]
	v_cvt_f32_u32_e32 v4, v2
	s_waitcnt vmcnt(0)
	v_readfirstlane_b32 s2, v3
	v_sub_u32_e32 v3, 0, v2
	v_rcp_iflag_f32_e32 v4, v4
	v_add_u32_e32 v5, s2, v1
	v_mul_f32_e32 v4, 0x4f7ffffe, v4
	v_cvt_u32_f32_e32 v4, v4
	v_mul_lo_u32 v1, v3, v4
	v_mul_hi_u32 v1, v4, v1
	v_add_u32_e32 v1, v4, v1
	v_mul_hi_u32 v1, v5, v1
	v_mul_lo_u32 v3, v1, v2
	v_sub_u32_e32 v3, v5, v3
	v_add_u32_e32 v4, 1, v1
	v_cmp_ge_u32_e32 vcc, v3, v2
	s_nop 1
	v_cndmask_b32_e32 v1, v1, v4, vcc
	v_sub_u32_e32 v4, v3, v2
	v_cndmask_b32_e32 v3, v3, v4, vcc
	v_add_u32_e32 v4, 1, v1
	v_cmp_ge_u32_e32 vcc, v3, v2
	v_add_u32_e32 v3, 1, v5
	s_nop 0
	v_cndmask_b32_e32 v1, v1, v4, vcc
	v_mul_lo_u32 v4, v2, v1
	v_add_u32_e32 v2, v4, v2
	v_cmp_ne_u32_e32 vcc, v3, v2
	s_and_saveexec_b64 s[2:3], vcc
	s_xor_b64 s[2:3], exec, s[2:3]
	s_cbranch_execz .LBB0_887
	s_waitcnt lgkmcnt(0)
	v_mov_b32_e32 v0, 0x2000
	global_load_dword v0, v0, s[4:5] offset:1024 sc1
	s_add_u32 s12, s4, 0x2400
	s_addc_u32 s13, s5, 0
	s_waitcnt vmcnt(0)
	v_cmp_eq_u32_e32 vcc, v0, v1
	s_and_saveexec_b64 s[6:7], vcc
	s_cbranch_execz .LBB0_886
	s_add_u32 s8, s18, 0x8200
	s_addc_u32 s9, s19, 0
	s_add_u32 s12, s18, 0xb500
	s_addc_u32 s13, s19, 0
	s_mov_b32 s28, 1
	s_mov_b64 s[14:15], 0
	v_mov_b32_e32 v0, 0
	s_branch .LBB0_877

.LBB0_983:
	s_or_b64 exec, exec, s[2:3]
	v_cvt_f32_u32_e32 v4, v2
	s_waitcnt vmcnt(0)
	v_readfirstlane_b32 s0, v3
	v_sub_u32_e32 v3, 0, v2
	v_rcp_iflag_f32_e32 v4, v4
	v_add_u32_e32 v5, s0, v1
	v_mul_f32_e32 v4, 0x4f7ffffe, v4
	v_cvt_u32_f32_e32 v4, v4
	v_mul_lo_u32 v1, v3, v4
	v_mul_hi_u32 v1, v4, v1
	v_add_u32_e32 v1, v4, v1
	v_mul_hi_u32 v1, v5, v1
	v_mul_lo_u32 v3, v1, v2
	v_sub_u32_e32 v3, v5, v3
	v_add_u32_e32 v4, 1, v1
	v_cmp_ge_u32_e32 vcc, v3, v2
	s_nop 1
	v_cndmask_b32_e32 v1, v1, v4, vcc
	v_sub_u32_e32 v4, v3, v2
	v_cndmask_b32_e32 v3, v3, v4, vcc
	v_add_u32_e32 v4, 1, v1
	v_cmp_ge_u32_e32 vcc, v3, v2
	v_add_u32_e32 v3, 1, v5
	s_nop 0
	v_cndmask_b32_e32 v1, v1, v4, vcc
	v_mul_lo_u32 v4, v2, v1
	v_add_u32_e32 v2, v4, v2
	v_cmp_ne_u32_e32 vcc, v3, v2
	s_and_saveexec_b64 s[0:1], vcc
	s_xor_b64 s[2:3], exec, s[0:1]
	s_cbranch_execz .LBB0_997
	s_waitcnt lgkmcnt(0)
	global_load_dword v0, v229, s[10:11] offset:1024 sc1
	s_add_u32 s12, s10, 0x2400
	s_addc_u32 s13, s11, 0
	s_waitcnt vmcnt(0)
	v_cmp_eq_u32_e32 vcc, v0, v1
	s_and_saveexec_b64 s[0:1], vcc
	s_cbranch_execz .LBB0_996
	s_add_u32 s6, s78, 0x8200
	s_addc_u32 s7, s79, 0
	s_add_u32 s12, s78, 0xb500
	s_addc_u32 s13, s79, 0
	s_mov_b32 s26, 1
	s_mov_b64 s[16:17], 0
	s_branch .LBB0_987

.LBB0_1079:
	s_or_b64 exec, exec, s[2:3]
	v_cvt_f32_u32_e32 v4, v2
	s_waitcnt vmcnt(0)
	v_readfirstlane_b32 s0, v3
	v_sub_u32_e32 v3, 0, v2
	v_rcp_iflag_f32_e32 v4, v4
	v_add_u32_e32 v5, s0, v1
	v_mul_f32_e32 v4, 0x4f7ffffe, v4
	v_cvt_u32_f32_e32 v4, v4
	v_mul_lo_u32 v1, v3, v4
	v_mul_hi_u32 v1, v4, v1
	v_add_u32_e32 v1, v4, v1
	v_mul_hi_u32 v1, v5, v1
	v_mul_lo_u32 v3, v1, v2
	v_sub_u32_e32 v3, v5, v3
	v_add_u32_e32 v4, 1, v1
	v_cmp_ge_u32_e32 vcc, v3, v2
	s_nop 1
	v_cndmask_b32_e32 v1, v1, v4, vcc
	v_sub_u32_e32 v4, v3, v2
	v_cndmask_b32_e32 v3, v3, v4, vcc
	v_add_u32_e32 v4, 1, v1
	v_cmp_ge_u32_e32 vcc, v3, v2
	v_add_u32_e32 v3, 1, v5
	s_nop 0
	v_cndmask_b32_e32 v1, v1, v4, vcc
	v_mul_lo_u32 v4, v2, v1
	v_add_u32_e32 v2, v4, v2
	v_cmp_ne_u32_e32 vcc, v3, v2
	s_and_saveexec_b64 s[0:1], vcc
	s_xor_b64 s[2:3], exec, s[0:1]
	s_cbranch_execz .LBB0_1093
	s_waitcnt lgkmcnt(0)
	global_load_dword v0, v229, s[10:11] offset:1024 sc1
	s_add_u32 s12, s10, 0x2400
	s_addc_u32 s13, s11, 0
	s_waitcnt vmcnt(0)
	v_cmp_eq_u32_e32 vcc, v0, v1
	s_and_saveexec_b64 s[6:7], vcc
	s_cbranch_execz .LBB0_1092
	s_add_u32 s8, s50, 0x8200
	s_addc_u32 s9, s51, 0
	s_add_u32 s12, s50, 0xb500
	s_addc_u32 s13, s51, 0
	s_mov_b32 s26, 1
	s_mov_b64 s[16:17], 0
	s_branch .LBB0_1083

.LBB0_1412:
	s_or_b64 exec, exec, s[2:3]
	v_cvt_f32_u32_e32 v4, v2
	s_waitcnt vmcnt(0)
	v_readfirstlane_b32 s0, v3
	v_sub_u32_e32 v3, 0, v2
	v_rcp_iflag_f32_e32 v4, v4
	v_add_u32_e32 v5, s0, v1
	v_mul_f32_e32 v4, 0x4f7ffffe, v4
	v_cvt_u32_f32_e32 v4, v4
	v_mul_lo_u32 v1, v3, v4
	v_mul_hi_u32 v1, v4, v1
	v_add_u32_e32 v1, v4, v1
	v_mul_hi_u32 v1, v5, v1
	v_mul_lo_u32 v3, v1, v2
	v_sub_u32_e32 v3, v5, v3
	v_add_u32_e32 v4, 1, v1
	v_cmp_ge_u32_e32 vcc, v3, v2
	s_nop 1
	v_cndmask_b32_e32 v1, v1, v4, vcc
	v_sub_u32_e32 v4, v3, v2
	v_cndmask_b32_e32 v3, v3, v4, vcc
	v_add_u32_e32 v4, 1, v1
	v_cmp_ge_u32_e32 vcc, v3, v2
	v_add_u32_e32 v3, 1, v5
	s_nop 0
	v_cndmask_b32_e32 v1, v1, v4, vcc
	v_mul_lo_u32 v4, v2, v1
	v_add_u32_e32 v2, v4, v2
	v_cmp_ne_u32_e32 vcc, v3, v2
	s_and_saveexec_b64 s[0:1], vcc
	s_xor_b64 s[2:3], exec, s[0:1]
	s_cbranch_execz .LBB0_1426
	s_waitcnt lgkmcnt(0)
	global_load_dword v0, v229, s[6:7] offset:1024 sc1
	s_add_u32 s10, s6, 0x2400
	s_addc_u32 s11, s7, 0
	s_waitcnt vmcnt(0)
	v_cmp_eq_u32_e32 vcc, v0, v1
	s_and_saveexec_b64 s[0:1], vcc
	s_cbranch_execz .LBB0_1425
	v_readlane_b32 s8, v255, 34
	v_readlane_b32 s9, v255, 35
	s_add_u32 s8, s8, 0x8200
	s_addc_u32 s9, s9, 0
	s_add_u32 s10, s8, 0xb500
	s_addc_u32 s11, s9, 0
	s_mov_b32 s26, 1
	s_mov_b64 s[16:17], 0
	s_branch .LBB0_1416

.LBB0_1474:
	s_or_b64 exec, exec, s[6:7]
	v_cvt_f32_u32_e32 v4, v2
	s_waitcnt vmcnt(0)
	v_readfirstlane_b32 s2, v3
	v_sub_u32_e32 v3, 0, v2
	v_rcp_iflag_f32_e32 v4, v4
	v_add_u32_e32 v5, s2, v1
	v_mul_f32_e32 v4, 0x4f7ffffe, v4
	v_cvt_u32_f32_e32 v4, v4
	v_mul_lo_u32 v1, v3, v4
	v_mul_hi_u32 v1, v4, v1
	v_add_u32_e32 v1, v4, v1
	v_mul_hi_u32 v1, v5, v1
	v_mul_lo_u32 v3, v1, v2
	v_sub_u32_e32 v3, v5, v3
	v_add_u32_e32 v4, 1, v1
	v_cmp_ge_u32_e32 vcc, v3, v2
	s_nop 1
	v_cndmask_b32_e32 v1, v1, v4, vcc
	v_sub_u32_e32 v4, v3, v2
	v_cndmask_b32_e32 v3, v3, v4, vcc
	v_add_u32_e32 v4, 1, v1
	v_cmp_ge_u32_e32 vcc, v3, v2
	v_add_u32_e32 v3, 1, v5
	s_nop 0
	v_cndmask_b32_e32 v1, v1, v4, vcc
	v_mul_lo_u32 v4, v2, v1
	v_add_u32_e32 v2, v4, v2
	v_cmp_ne_u32_e32 vcc, v3, v2
	s_and_saveexec_b64 s[2:3], vcc
	s_xor_b64 s[2:3], exec, s[2:3]
	s_cbranch_execz .LBB0_1488
	s_waitcnt lgkmcnt(0)
	global_load_dword v0, v229, s[8:9] offset:1024 sc1
	s_add_u32 s12, s8, 0x2400
	s_addc_u32 s13, s9, 0
	s_waitcnt vmcnt(0)
	v_cmp_eq_u32_e32 vcc, v0, v1
	s_and_saveexec_b64 s[6:7], vcc
	s_cbranch_execz .LBB0_1487
	s_add_u32 s10, s0, 0x8200
	s_addc_u32 s11, s1, 0
	s_add_u32 s12, s0, 0xb500
	s_addc_u32 s13, s1, 0
	s_mov_b32 s33, 1
	s_mov_b64 s[16:17], 0
	s_branch .LBB0_1478

.LBB0_1639:
	s_or_b64 exec, exec, s[2:3]
	v_cvt_f32_u32_e32 v4, v2
	s_waitcnt vmcnt(0)
	v_readfirstlane_b32 s0, v3
	v_sub_u32_e32 v3, 0, v2
	v_rcp_iflag_f32_e32 v4, v4
	v_add_u32_e32 v5, s0, v1
	v_mul_f32_e32 v4, 0x4f7ffffe, v4
	v_cvt_u32_f32_e32 v4, v4
	v_mul_lo_u32 v1, v3, v4
	v_mul_hi_u32 v1, v4, v1
	v_add_u32_e32 v1, v4, v1
	v_mul_hi_u32 v1, v5, v1
	v_mul_lo_u32 v3, v1, v2
	v_sub_u32_e32 v3, v5, v3
	v_add_u32_e32 v4, 1, v1
	v_cmp_ge_u32_e32 vcc, v3, v2
	s_nop 1
	v_cndmask_b32_e32 v1, v1, v4, vcc
	v_sub_u32_e32 v4, v3, v2
	v_cndmask_b32_e32 v3, v3, v4, vcc
	v_add_u32_e32 v4, 1, v1
	v_cmp_ge_u32_e32 vcc, v3, v2
	v_add_u32_e32 v3, 1, v5
	s_nop 0
	v_cndmask_b32_e32 v1, v1, v4, vcc
	v_mul_lo_u32 v4, v2, v1
	v_add_u32_e32 v2, v4, v2
	v_cmp_ne_u32_e32 vcc, v3, v2
	s_and_saveexec_b64 s[0:1], vcc
	s_xor_b64 s[2:3], exec, s[0:1]
	s_cbranch_execz .LBB0_1653
	s_waitcnt lgkmcnt(0)
	global_load_dword v0, v229, s[6:7] offset:1024 sc1
	s_add_u32 s10, s6, 0x2400
	s_addc_u32 s11, s7, 0
	s_waitcnt vmcnt(0)
	v_cmp_eq_u32_e32 vcc, v0, v1
	s_and_saveexec_b64 s[0:1], vcc
	s_cbranch_execz .LBB0_1652
	s_add_u32 s8, s18, 0x8200
	s_addc_u32 s9, s19, 0
	s_add_u32 s10, s18, 0xb500
	s_addc_u32 s11, s19, 0
	s_mov_b32 s33, 1
	s_mov_b64 s[12:13], 0
	s_branch .LBB0_1643

.LBB0_1774:
	s_or_b64 exec, exec, s[2:3]
	v_cvt_f32_u32_e32 v4, v2
	s_waitcnt vmcnt(0)
	v_readfirstlane_b32 s0, v3
	v_sub_u32_e32 v3, 0, v2
	v_rcp_iflag_f32_e32 v4, v4
	v_add_u32_e32 v5, s0, v1
	v_mul_f32_e32 v4, 0x4f7ffffe, v4
	v_cvt_u32_f32_e32 v4, v4
	v_mul_lo_u32 v1, v3, v4
	v_mul_hi_u32 v1, v4, v1
	v_add_u32_e32 v1, v4, v1
	v_mul_hi_u32 v1, v5, v1
	v_mul_lo_u32 v3, v1, v2
	v_sub_u32_e32 v3, v5, v3
	v_add_u32_e32 v4, 1, v1
	v_cmp_ge_u32_e32 vcc, v3, v2
	s_nop 1
	v_cndmask_b32_e32 v1, v1, v4, vcc
	v_sub_u32_e32 v4, v3, v2
	v_cndmask_b32_e32 v3, v3, v4, vcc
	v_add_u32_e32 v4, 1, v1
	v_cmp_ge_u32_e32 vcc, v3, v2
	v_add_u32_e32 v3, 1, v5
	s_nop 0
	v_cndmask_b32_e32 v1, v1, v4, vcc
	v_mul_lo_u32 v4, v2, v1
	v_add_u32_e32 v2, v4, v2
	v_cmp_ne_u32_e32 vcc, v3, v2
	s_and_saveexec_b64 s[0:1], vcc
	s_xor_b64 s[2:3], exec, s[0:1]
	s_cbranch_execz .LBB0_1788
	s_waitcnt lgkmcnt(0)
	global_load_dword v0, v229, s[8:9] offset:1024 sc1
	s_add_u32 s16, s8, 0x2400
	s_addc_u32 s17, s9, 0
	s_waitcnt vmcnt(0)
	v_cmp_eq_u32_e32 vcc, v0, v1
	s_and_saveexec_b64 s[10:11], vcc
	s_cbranch_execz .LBB0_1787
	s_add_u32 s12, s28, 0x8200
	s_addc_u32 s13, s29, 0
	s_add_u32 s16, s28, 0xb500
	s_addc_u32 s17, s29, 0
	s_mov_b32 s26, 1
	s_mov_b64 s[18:19], 0
	s_branch .LBB0_1778

.LBB0_1869:
	s_or_b64 exec, exec, s[2:3]
	v_cvt_f32_u32_e32 v4, v2
	s_waitcnt vmcnt(0)
	v_readfirstlane_b32 s0, v3
	v_sub_u32_e32 v3, 0, v2
	v_rcp_iflag_f32_e32 v4, v4
	v_add_u32_e32 v5, s0, v1
	v_mul_f32_e32 v4, 0x4f7ffffe, v4
	v_cvt_u32_f32_e32 v4, v4
	v_mul_lo_u32 v1, v3, v4
	v_mul_hi_u32 v1, v4, v1
	v_add_u32_e32 v1, v4, v1
	v_mul_hi_u32 v1, v5, v1
	v_mul_lo_u32 v3, v1, v2
	v_sub_u32_e32 v3, v5, v3
	v_add_u32_e32 v4, 1, v1
	v_cmp_ge_u32_e32 vcc, v3, v2
	s_nop 1
	v_cndmask_b32_e32 v1, v1, v4, vcc
	v_sub_u32_e32 v4, v3, v2
	v_cndmask_b32_e32 v3, v3, v4, vcc
	v_add_u32_e32 v4, 1, v1
	v_cmp_ge_u32_e32 vcc, v3, v2
	v_add_u32_e32 v3, 1, v5
	s_nop 0
	v_cndmask_b32_e32 v1, v1, v4, vcc
	v_mul_lo_u32 v4, v2, v1
	v_add_u32_e32 v2, v4, v2
	v_cmp_ne_u32_e32 vcc, v3, v2
	s_and_saveexec_b64 s[0:1], vcc
	s_xor_b64 s[2:3], exec, s[0:1]
	s_cbranch_execz .LBB0_1883
	s_waitcnt lgkmcnt(0)
	global_load_dword v0, v229, s[6:7] offset:1024 sc1
	s_add_u32 s12, s6, 0x2400
	s_addc_u32 s13, s7, 0
	s_waitcnt vmcnt(0)
	v_cmp_eq_u32_e32 vcc, v0, v1
	s_and_saveexec_b64 s[8:9], vcc
	s_cbranch_execz .LBB0_1882
	s_add_u32 s10, s18, 0x8200
	s_addc_u32 s11, s19, 0
	s_add_u32 s12, s18, 0xb500
	s_addc_u32 s13, s19, 0
	s_mov_b32 s36, 1
	s_mov_b64 s[16:17], 0
	s_branch .LBB0_1873

.LBB0_1942:
	s_or_b64 exec, exec, s[2:3]
	v_cvt_f32_u32_e32 v4, v2
	s_waitcnt vmcnt(0)
	v_readfirstlane_b32 s0, v3
	v_sub_u32_e32 v3, 0, v2
	v_rcp_iflag_f32_e32 v4, v4
	v_add_u32_e32 v5, s0, v1
	v_mul_f32_e32 v4, 0x4f7ffffe, v4
	v_cvt_u32_f32_e32 v4, v4
	v_mul_lo_u32 v1, v3, v4
	v_mul_hi_u32 v1, v4, v1
	v_add_u32_e32 v1, v4, v1
	v_mul_hi_u32 v1, v5, v1
	v_mul_lo_u32 v3, v1, v2
	v_sub_u32_e32 v3, v5, v3
	v_add_u32_e32 v4, 1, v1
	v_cmp_ge_u32_e32 vcc, v3, v2
	s_nop 1
	v_cndmask_b32_e32 v1, v1, v4, vcc
	v_sub_u32_e32 v4, v3, v2
	v_cndmask_b32_e32 v3, v3, v4, vcc
	v_add_u32_e32 v4, 1, v1
	v_cmp_ge_u32_e32 vcc, v3, v2
	v_add_u32_e32 v3, 1, v5
	s_nop 0
	v_cndmask_b32_e32 v1, v1, v4, vcc
	v_mul_lo_u32 v4, v2, v1
	v_add_u32_e32 v2, v4, v2
	v_cmp_ne_u32_e32 vcc, v3, v2
	s_and_saveexec_b64 s[0:1], vcc
	s_xor_b64 s[2:3], exec, s[0:1]
	s_cbranch_execz .LBB0_1956
	s_waitcnt lgkmcnt(0)
	global_load_dword v0, v229, s[8:9] offset:1024 sc1
	s_add_u32 s16, s8, 0x2400
	s_addc_u32 s17, s9, 0
	s_waitcnt vmcnt(0)
	v_cmp_eq_u32_e32 vcc, v0, v1
	s_and_saveexec_b64 s[10:11], vcc
	s_cbranch_execz .LBB0_1955
	s_add_u32 s12, s28, 0x8200
	s_addc_u32 s13, s29, 0
	s_add_u32 s16, s28, 0xb500
	s_addc_u32 s17, s29, 0
	s_mov_b32 s36, 1
	s_mov_b64 s[18:19], 0
	s_branch .LBB0_1946

.LBB0_2071:
	s_or_b64 exec, exec, s[2:3]
	v_cvt_f32_u32_e32 v4, v2
	s_waitcnt vmcnt(0)
	v_readfirstlane_b32 s0, v3
	v_sub_u32_e32 v3, 0, v2
	v_rcp_iflag_f32_e32 v4, v4
	v_add_u32_e32 v5, s0, v1
	v_mul_f32_e32 v4, 0x4f7ffffe, v4
	v_cvt_u32_f32_e32 v4, v4
	v_mul_lo_u32 v1, v3, v4
	v_mul_hi_u32 v1, v4, v1
	v_add_u32_e32 v1, v4, v1
	v_mul_hi_u32 v1, v5, v1
	v_mul_lo_u32 v3, v1, v2
	v_sub_u32_e32 v3, v5, v3
	v_add_u32_e32 v4, 1, v1
	v_cmp_ge_u32_e32 vcc, v3, v2
	s_nop 1
	v_cndmask_b32_e32 v1, v1, v4, vcc
	v_sub_u32_e32 v4, v3, v2
	v_cndmask_b32_e32 v3, v3, v4, vcc
	v_add_u32_e32 v4, 1, v1
	v_cmp_ge_u32_e32 vcc, v3, v2
	v_add_u32_e32 v3, 1, v5
	s_nop 0
	v_cndmask_b32_e32 v1, v1, v4, vcc
	v_mul_lo_u32 v4, v2, v1
	v_add_u32_e32 v2, v4, v2
	v_cmp_ne_u32_e32 vcc, v3, v2
	s_and_saveexec_b64 s[0:1], vcc
	s_xor_b64 s[2:3], exec, s[0:1]
	s_cbranch_execz .LBB0_2085
	s_waitcnt lgkmcnt(0)
	global_load_dword v0, v229, s[6:7] offset:1024 sc1
	s_add_u32 s12, s6, 0x2400
	s_addc_u32 s13, s7, 0
	s_waitcnt vmcnt(0)
	v_cmp_eq_u32_e32 vcc, v0, v1
	s_and_saveexec_b64 s[8:9], vcc
	s_cbranch_execz .LBB0_2084
	s_add_u32 s10, s18, 0x8200
	s_addc_u32 s11, s19, 0
	s_add_u32 s12, s18, 0xb500
	s_addc_u32 s13, s19, 0
	s_mov_b32 s33, 1
	s_mov_b64 s[16:17], 0
	s_branch .LBB0_2075

.LBB0_2134:
	s_or_b64 exec, exec, s[8:9]
	v_cvt_f32_u32_e32 v4, v2
	s_waitcnt vmcnt(0)
	v_readfirstlane_b32 s6, v3
	v_sub_u32_e32 v3, 0, v2
	v_rcp_iflag_f32_e32 v4, v4
	v_add_u32_e32 v5, s6, v1
	v_mul_f32_e32 v4, 0x4f7ffffe, v4
	v_cvt_u32_f32_e32 v4, v4
	v_mul_lo_u32 v1, v3, v4
	v_mul_hi_u32 v1, v4, v1
	v_add_u32_e32 v1, v4, v1
	v_mul_hi_u32 v1, v5, v1
	v_mul_lo_u32 v3, v1, v2
	v_sub_u32_e32 v3, v5, v3
	v_add_u32_e32 v4, 1, v1
	v_cmp_ge_u32_e32 vcc, v3, v2
	s_nop 1
	v_cndmask_b32_e32 v1, v1, v4, vcc
	v_sub_u32_e32 v4, v3, v2
	v_cndmask_b32_e32 v3, v3, v4, vcc
	v_add_u32_e32 v4, 1, v1
	v_cmp_ge_u32_e32 vcc, v3, v2
	v_add_u32_e32 v3, 1, v5
	s_nop 0
	v_cndmask_b32_e32 v1, v1, v4, vcc
	v_mul_lo_u32 v4, v2, v1
	v_add_u32_e32 v2, v4, v2
	v_cmp_ne_u32_e32 vcc, v3, v2
	s_and_saveexec_b64 s[6:7], vcc
	s_xor_b64 s[6:7], exec, s[6:7]
	s_cbranch_execz .LBB0_2148
	s_waitcnt lgkmcnt(0)
	v_mov_b32_e32 v0, 0x2000
	global_load_dword v0, v0, s[4:5] offset:1024 sc1
	s_add_u32 s12, s4, 0x2400
	s_addc_u32 s13, s5, 0
	s_waitcnt vmcnt(0)
	v_cmp_eq_u32_e32 vcc, v0, v1
	s_and_saveexec_b64 s[8:9], vcc
	s_cbranch_execz .LBB0_2147
	s_add_u32 s10, s2, 0x8200
	s_addc_u32 s11, s3, 0
	s_add_u32 s12, s2, 0xb500
	s_addc_u32 s13, s3, 0
	s_mov_b32 s24, 1
	s_mov_b64 s[14:15], 0
	v_mov_b32_e32 v0, 0
	s_branch .LBB0_2138
